# v28 + SSM pass-B waits vmcnt(1) (store stays in flight) + SB K-fragment LDS reads hoisted above V writes and prefetch issue
# speedup vs baseline: 1.0153x; 1.0029x over previous
; __device__ __forceinline__ unsigned pk2(float lo, float hi) { return pg8::cvt_pk_bf16(lo, hi); }
; __device__ __forceinline__ void sb_mfma(const bf16_t* __restrict__ proj, bf16_t* __restrict__ mix, LAS unsigned char* ldsl) {
;     ...
;             frag_read(kf, kimg, r32, hi);
;             f32x16 s;
; #pragma unroll
;             for (int r = 0; r < 16; ++r) s[r] = 0.f;
; #pragma unroll
;             for (int d0 = 0; d0 < 4; ++d0) s = __builtin_amdgcn_mfma_f32_32x32x16_bf16(as_bf(kf[d0]), as_bf(qf[d0]), s, 0, 0, 0);
;             const bool diag = (kb == t0);
;             float bt[16], kp1[16];
; #pragma unroll
;             for (int r = 0; r < 16; ++r) {
;                 const float z = fmaxf(s[r], -126.f);
;                 const float a = __builtin_amdgcn_exp2f(-z), rc = __builtin_amdgcn_rcpf(1.f + a);
;                 float be = rc, ke = a * rc;
;                 if (diag) { const bool valid = crow(r, hi) < r32; be = valid ? be : 0.f; ke = valid ? ke : 1.f; }
;                 bt[r] = be; kp1[r] = ke;
;             }
;             float gs[4], X[4];
; #pragma unroll
;             for (int c = 0; c < 4; ++c) { const float g4 = (kp1[4 * c] * kp1[4 * c + 1]) * (kp1[4 * c + 2] * kp1[4 * c + 3]); const HalfPair hp = half_swap(g4);
;                 gs[c] = hp.a * hp.b; X[c] = hi == 0 ? hp.b : 1.f; }
;             const float S2 = gs[3], S1 = S2 * gs[2], S0 = S1 * gs[1], total = S0 * gs[0];
;             const float SS[4] = {S0, S1, S2, 1.f};
;             float w[16];
; #pragma unroll
;             for (int c = 0; c < 4; ++c) {
;                 float run = A * SS[c] * X[c];
;                 w[4 * c + 3] = bt[4 * c + 3] * run; run *= kp1[4 * c + 3];
;                 w[4 * c + 2] = bt[4 * c + 2] * run; run *= kp1[4 * c + 2];
;                 w[4 * c + 1] = bt[4 * c + 1] * run; run *= kp1[4 * c + 1];
;                 w[4 * c + 0] = bt[4 * c + 0] * run;
;             }
;             A *= total;
;             u32x4 pb[2];
; #pragma unroll
;             for (int kk = 0; kk < 2; ++kk) { pb[kk].x = pk2(w[8 * kk], w[8 * kk + 1]); pb[kk].y = pk2(w[8 * kk + 2], w[8 * kk + 3]);
;                 pb[kk].z = pk2(w[8 * kk + 4], w[8 * kk + 5]); pb[kk].w = pk2(w[8 * kk + 6], w[8 * kk + 7]); }
;             pv_tile_tr(vimg, pb, o0, o1, r32, hi);
;             if (__all(A < 1.17549435e-38f)) break;
.LBB0_275:
	s_waitcnt lgkmcnt(7)
	v_mfma_f32_32x32x16_bf16 v[32:47], v[118:121], v[48:51], 0
	s_waitcnt lgkmcnt(6)
	v_mfma_f32_32x32x16_bf16 v[32:47], v[110:113], v[52:55], v[32:47]
	s_waitcnt lgkmcnt(5)
	v_mfma_f32_32x32x16_bf16 v[32:47], v[122:125], v[56:59], v[32:47]
	s_waitcnt lgkmcnt(4)
	v_mfma_f32_32x32x16_bf16 v[32:47], v[114:117], v[60:63], v[32:47]
	s_nop 11
	v_max_f32_e64 v44, -v44, -v44
	v_max_f32_e64 v32, -v32, -v32
	v_max_f32_e64 v37, -v37, -v37
	v_max_f32_e64 v38, -v38, -v38
	v_min_f32_e32 v44, 0x42fc0000, v44
	v_max_f32_e64 v39, -v39, -v39
	v_min_f32_e32 v32, 0x42fc0000, v32
	v_min_f32_e32 v37, 0x42fc0000, v37
	v_min_f32_e32 v105, 0x42fc0000, v38
	v_exp_f32_e32 v44, v44
	v_min_f32_e32 v39, 0x42fc0000, v39
	v_exp_f32_e32 v32, v32
	v_exp_f32_e32 v38, v37
	v_exp_f32_e32 v37, v105
	v_exp_f32_e32 v39, v39
	v_max_f32_e64 v45, -v45, -v45
	v_max_f32_e64 v33, -v33, -v33
	v_min_f32_e32 v45, 0x42fc0000, v45
	v_max_f32_e64 v34, -v34, -v34
	v_max_f32_e64 v40, -v40, -v40
	v_min_f32_e32 v33, 0x42fc0000, v33
	v_exp_f32_e32 v122, v45
	v_add_f32_e32 v45, 1.0, v44
	v_min_f32_e32 v103, 0x42fc0000, v34
	v_min_f32_e32 v109, 0x42fc0000, v40
	v_exp_f32_e32 v34, v33
	v_add_f32_e32 v40, 1.0, v32
	v_add_f32_e32 v115, 1.0, v38
	v_add_f32_e32 v116, 1.0, v37
	v_max_f32_e64 v41, -v41, -v41
	v_max_f32_e64 v42, -v42, -v42
	v_rcp_f32_e32 v124, v45
	v_max_f32_e64 v45, -v46, -v46
	v_add_f32_e32 v117, 1.0, v39
	v_rcp_f32_e32 v110, v40
	v_rcp_f32_e32 v40, v115
	v_rcp_f32_e32 v115, v116
	v_exp_f32_e32 v116, v109
	v_min_f32_e32 v41, 0x42fc0000, v41
	v_min_f32_e32 v42, 0x42fc0000, v42
	v_min_f32_e32 v45, 0x42fc0000, v45
	v_max_f32_e64 v46, -v47, -v47
	v_exp_f32_e32 v118, v41
	v_rcp_f32_e32 v41, v117
	v_exp_f32_e32 v117, v42
	v_max_f32_e64 v42, -v43, -v43
	v_exp_f32_e32 v45, v45
	v_min_f32_e32 v46, 0x42fc0000, v46
	v_min_f32_e32 v42, 0x42fc0000, v42
	v_exp_f32_e32 v123, v46
	v_max_f32_e64 v36, -v36, -v36
	v_exp_f32_e32 v33, v103
	v_add_f32_e32 v103, 1.0, v34
	v_exp_f32_e32 v119, v42
	v_min_f32_e32 v36, 0x42fc0000, v36
	v_rcp_f32_e32 v112, v103
	v_add_f32_e32 v103, 1.0, v116
	v_max_f32_e64 v35, -v35, -v35
	v_exp_f32_e32 v36, v36
	v_rcp_f32_e32 v120, v103
	v_add_f32_e32 v103, 1.0, v118
	v_add_f32_e32 v47, 1.0, v45
	v_min_f32_e32 v35, 0x42fc0000, v35
	v_rcp_f32_e32 v42, v103
	v_add_f32_e32 v43, 1.0, v117
	v_add_f32_e32 v103, 1.0, v122
	v_rcp_f32_e32 v125, v47
	v_add_f32_e32 v47, 1.0, v123
	v_exp_f32_e32 v35, v35
	v_rcp_f32_e32 v121, v43
	v_add_f32_e32 v43, 1.0, v119
	v_rcp_f32_e32 v46, v103
	v_rcp_f32_e32 v47, v47
	v_rcp_f32_e32 v43, v43
	v_add_f32_e32 v114, 1.0, v36
	v_rcp_f32_e32 v114, v114
	v_add_f32_e32 v105, 1.0, v33
	v_add_f32_e32 v113, 1.0, v35
	v_pk_mul_f32 v[44:45], v[44:45], v[124:125]
	v_pk_mul_f32 v[122:123], v[122:123], v[46:47]
	v_rcp_f32_e32 v111, v105
	v_rcp_f32_e32 v113, v113
	v_pk_mul_f32 v[116:117], v[116:117], v[120:121]
	v_pk_mul_f32 v[118:119], v[118:119], v[42:43]
	v_pk_mul_f32 v[138:139], v[44:45], v[122:123]
	v_pk_mul_f32 v[134:135], v[116:117], v[118:119]
	v_pk_mul_f32 v[138:139], v[138:139], v[138:139] op_sel:[0,1] op_sel_hi:[1,0]
	v_pk_mul_f32 v[36:37], v[36:37], v[114:115]
	v_pk_mul_f32 v[38:39], v[38:39], v[40:41]
	v_pk_mul_f32 v[134:135], v[134:135], v[134:135] op_sel:[0,1] op_sel_hi:[1,0]
	v_mov_b32_e32 v137, v138
	v_pk_mul_f32 v[130:131], v[36:37], v[38:39]
	v_mov_b32_e32 v136, v134
	v_permlane32_swap_b32_e32 v138, v137
	v_pk_mul_f32 v[32:33], v[32:33], v[110:111]
	v_pk_mul_f32 v[34:35], v[34:35], v[112:113]
	v_pk_mul_f32 v[130:131], v[130:131], v[130:131] op_sel:[0,1] op_sel_hi:[1,0]
	v_permlane32_swap_b32_e32 v134, v136
	v_mov_b32_e32 v135, v138
	v_pk_mul_f32 v[126:127], v[32:33], v[34:35]
	v_mov_b32_e32 v132, v130
	v_pk_mul_f32 v[134:135], v[134:135], v[136:137]
	v_pk_mul_f32 v[126:127], v[126:127], v[126:127] op_sel:[0,1] op_sel_hi:[1,0]
	v_permlane32_swap_b32_e32 v130, v132
	v_mov_b32_e32 v131, v134
	v_mov_b32_e32 v133, v135
	v_mov_b32_e32 v128, v126
	v_pk_mul_f32 v[130:131], v[130:131], v[132:133]
	s_nop 0
	v_permlane32_swap_b32_e32 v126, v128
	v_mov_b32_e32 v127, v130
	v_mov_b32_e32 v129, v131
	v_pk_mul_f32 v[126:127], v[126:127], v[128:129]
	v_cndmask_b32_e64 v32, 1.0, v128, s[0:1]
	v_mul_f32_e32 v105, v101, v127
	v_mul_f32_e32 v32, v32, v105
	v_mul_f32_e32 v105, v113, v32
	v_mul_f32_e32 v32, v35, v32
	v_mul_f32_e32 v35, v111, v32
	v_mul_f32_e32 v32, v33, v32
	v_cndmask_b32_e64 v36, 1.0, v132, s[0:1]
	v_mul_f32_e32 v33, v112, v32
	v_mul_f32_e32 v32, v34, v32
	v_mul_f32_e32 v34, v101, v131
	v_mul_f32_e32 v34, v36, v34
	v_mul_f32_e32 v36, v41, v34
	v_mul_f32_e32 v34, v39, v34
	v_mul_f32_e32 v39, v115, v34
	v_mul_f32_e32 v34, v37, v34
	v_cndmask_b32_e64 v44, 1.0, v136, s[0:1]
	v_mul_f32_e32 v37, v40, v34
	v_mul_f32_e32 v34, v38, v34
	v_mul_f32_e32 v38, v101, v135
	v_cndmask_b32_e64 v103, 1.0, v137, s[0:1]
	v_mul_f32_e32 v38, v44, v38
	v_mul_f32_e32 v40, v43, v38
	v_mul_f32_e32 v43, v101, v103
	v_mul_f32_e32 v38, v119, v38
	v_mul_f32_e32 v44, v47, v43
	v_mul_f32_e32 v43, v123, v43
	v_mul_f32_e32 v41, v121, v38
	v_mul_f32_e32 v38, v117, v38
	v_mul_f32_e32 v47, v125, v43
	v_mul_f32_e32 v43, v45, v43
	v_mul_f32_e32 v42, v42, v38
	v_mul_f32_e32 v38, v118, v38
	v_mul_f32_e32 v45, v46, v43
	v_mul_f32_e32 v43, v122, v43
	v_mul_f32_e32 v32, v110, v32
	v_mul_f32_e32 v34, v114, v34
	v_mul_f32_e32 v38, v120, v38
	v_mul_f32_e32 v43, v124, v43
	v_cvt_pk_bf16_f32 v32, v32, v33
	v_cvt_pk_bf16_f32 v33, v35, v105
	v_cvt_pk_bf16_f32 v34, v34, v37
	v_cvt_pk_bf16_f32 v35, v39, v36
	v_cvt_pk_bf16_f32 v36, v38, v42
	v_cvt_pk_bf16_f32 v37, v41, v40
	v_cvt_pk_bf16_f32 v38, v43, v45
	v_cvt_pk_bf16_f32 v39, v47, v44
	ds_read_b64_tr_b16 v[40:41], v108 offset:4608
	ds_read_b64_tr_b16 v[42:43], v108 offset:5760
	ds_read_b64_tr_b16 v[46:47], v108 offset:5824
	ds_read_b64_tr_b16 v[44:45], v108 offset:4672
	s_waitcnt lgkmcnt(2)
	v_mfma_f32_32x32x16_bf16 v[16:31], v[40:43], v[32:35], v[16:31]
	s_waitcnt lgkmcnt(0)
	v_mfma_f32_32x32x16_bf16 v[0:15], v[44:47], v[32:35], v[0:15]
	ds_read_b64_tr_b16 v[32:33], v108 offset:6912
	ds_read_b64_tr_b16 v[34:35], v108 offset:8064
	ds_read_b64_tr_b16 v[42:43], v108 offset:8128
	ds_read_b64_tr_b16 v[40:41], v108 offset:6976
	s_waitcnt lgkmcnt(2)
	v_mfma_f32_32x32x16_bf16 v[16:31], v[32:35], v[36:39], v[16:31]
	v_mul_f32_e32 v32, v126, v127
	v_mul_f32_e32 v101, v101, v32
	v_cmp_gt_f32_e32 vcc, s3, v101
	s_cmp_lg_u64 vcc, exec
	s_cselect_b64 s[50:51], -1, 0
	s_cmp_gt_u32 s48, 63
	s_cselect_b64 s[66:67], -1, 0
	s_waitcnt lgkmcnt(0)
	v_mfma_f32_32x32x16_bf16 v[0:15], v[40:43], v[36:39], v[0:15]
	s_and_b64 s[50:51], s[66:67], s[50:51]
	s_sub_i32 s48, s48, 32
	s_and_b64 vcc, exec, s[50:51]
	s_cbranch_vccz .LBB0_271
; __device__ __forceinline__ void sb_mfma(const bf16_t* __restrict__ proj, bf16_t* __restrict__ mix, LAS unsigned char* ldsl) {
;     ...
;             tile_to_lds(kimg, kt, lane);
;             tile_to_lds(vimg, vt4, lane);
;             if (kb >= 32) {
;                 tile_load(kt, hb + (size_t)(kb - 32) * 3072 + 1024, 3072, lane);
;                 tile_load(vt4, hb + (size_t)(kb - 32) * 3072 + 2048, 3072, lane);
;             }
;             u32x4 kf[4];
;             frag_read(kf, kimg, r32, hi);
.LBB0_276:
	s_cmp_eq_u32 s48, 32
	s_waitcnt vmcnt(7)
	ds_write_b128 v106, v[64:67]
	s_waitcnt vmcnt(6)
	ds_write_b128 v106, v[68:71] offset:1152
	s_waitcnt vmcnt(5)
	ds_write_b128 v106, v[72:75] offset:2304
	s_waitcnt vmcnt(4)
	ds_write_b128 v106, v[76:79] offset:3456
	ds_read_b128 v[118:121], v107
	ds_read_b128 v[110:113], v107 offset:32
	ds_read_b128 v[122:125], v107 offset:64
	ds_read_b128 v[114:117], v107 offset:96
	s_waitcnt vmcnt(3)
	ds_write_b128 v106, v[80:83] offset:4608
	s_waitcnt vmcnt(2)
	ds_write_b128 v106, v[84:87] offset:5760
	s_waitcnt vmcnt(1)
	ds_write_b128 v106, v[88:91] offset:6912
	s_waitcnt vmcnt(0)
	ds_write_b128 v106, v[92:95] offset:8064
	s_cbranch_scc1 .LBB0_275
	s_sub_i32 s49, s48, 64
	s_mul_hi_u32 s51, s49, 0x1800
	s_mulk_i32 s49, 0x1800
	s_add_u32 s50, s41, s49
	s_addc_u32 s51, s47, s51
	v_lshl_add_u64 v[32:33], s[50:51], 0, v[148:149]
	v_mov_b32_e32 v105, v149
	v_lshl_add_u64 v[32:33], v[32:33], 0, v[104:105]
	v_add_co_u32_e32 v34, vcc, s56, v32
	s_nop 1
	v_addc_co_u32_e32 v35, vcc, 0, v33, vcc
	global_load_dwordx4 v[64:67], v[32:33], off offset:2048
	global_load_dwordx4 v[68:71], v[34:35], off offset:2048
	v_add_co_u32_e32 v34, vcc, s60, v32
	s_nop 1
	v_addc_co_u32_e32 v35, vcc, 0, v33, vcc
	v_add_co_u32_e32 v36, vcc, s33, v32
	s_nop 1
	v_addc_co_u32_e32 v37, vcc, 0, v33, vcc
	global_load_dwordx4 v[72:75], v[34:35], off offset:2048
	global_load_dwordx4 v[76:79], v[36:37], off offset:2048
	v_add_co_u32_e32 v34, vcc, 0x1000, v32
	s_nop 1
	v_addc_co_u32_e32 v35, vcc, 0, v33, vcc
	v_add_co_u32_e32 v36, vcc, 0xd000, v32
	s_nop 1
	v_addc_co_u32_e32 v37, vcc, 0, v33, vcc
	global_load_dwordx4 v[80:83], v[34:35], off
	global_load_dwordx4 v[84:87], v[36:37], off
	v_add_co_u32_e32 v34, vcc, 0x19000, v32
	s_nop 1
	v_addc_co_u32_e32 v35, vcc, 0, v33, vcc
	v_add_co_u32_e32 v32, vcc, 0x25000, v32
	s_nop 1
	v_addc_co_u32_e32 v33, vcc, 0, v33, vcc
	global_load_dwordx4 v[88:91], v[34:35], off
	global_load_dwordx4 v[92:95], v[32:33], off
	s_branch .LBB0_275
